# dk64 K tile swizzle keyed on (row>>1)&7: conflict-free ds_read_b128 groups
# speedup vs baseline: 1.0007x; 1.0007x over previous
; DI unsigned cvt_pk_bf16(float lo, float hi) { unsigned r; asm volatile("v_cvt_pk_bf16_f32 %0, %1, %2" : "=v"(r) : "v"(lo), "v"(hi)); return r; }
; DI float bf_lo(unsigned w) { return __uint_as_float(w << 16); }
; DI float bf_hi(unsigned w) { return __uint_as_float(w & 0xffff0000u); }
; template <int DK>
; DI void attn_pass(const AttnSrc& s, const int q0, const float sc, LAS unsigned char* lds, f32x16 (&O)[4]) {
;     ...
;   for (int i = 0; i < KP; ++i) {
;     const int o = (wid + 8 * i) * 1024 + lane * 16, row = o / ROWB, pc = (o % ROWB) >> 4;
;     const int lc = (DK == 64) ? (pc ^ (row & 7)) : ((pc & ~7) | ((pc & 7) ^ ((row >> 1) & 7)));
;     const int e = lc * 8;
;     if (e < s.nk0) { kp[i] = s.k0 + (size_t)row * s.ldk0 + e; kstr[i] = 64 * s.ldk0; } else { kp[i] = s.k1 + (size_t)row * s.ldk1 + (e - s.nk0); kstr[i] = 64 * s.ldk1; }
;   }
; #pragma unroll
;   for (int i = 0; i < 2; ++i) {
;     const int o = (wid + 8 * i) * 1024 + lane * 16, row = o >> 8, pc = (o >> 4) & 15;
;     const int lc = (((pc >> 2) ^ (row & 3)) << 2) | (pc & 3);
;     vp[i] = s.v + (size_t)row * s.ldv + lc * 8;
;   }
;   const int vstr = 64 * s.ldv;
;   const unsigned lds0 = (unsigned)reinterpret_cast<__UINTPTR_TYPE__>(lds);
;   auto issue = [&](int t, int buf) {
; #pragma unroll
;     for (int i = 0; i < KP; ++i) glds16(kp[i] + (size_t)t * kstr[i], (unsigned)__builtin_amdgcn_readfirstlane(lds0 + buf * STG + (wid + 8 * i) * 1024));
; #pragma unroll
;     for (int i = 0; i < 2; ++i) glds16(vp[i] + (size_t)t * vstr, (unsigned)__builtin_amdgcn_readfirstlane(lds0 + buf * STG + KSZ + (wid + 8 * i) * 1024));
;   };
; #pragma unroll
;   for (int i = 0; i < DPF; ++i) issue(i, i);
;   bf16x8 qf[NS];
; #pragma unroll
;   for (int i = 0; i < NS; ++i) qf[i] = *(const bf16x8*)(s.q + (size_t)(qw0 + r) * s.ldq + 16 * i + 8 * h);
; #pragma unroll
;   for (int i = 0; i < NS; ++i) asm volatile("" : "+v"(qf[i]));
;   constexpr bool REL = (DK == 64);
;   if (REL) {
; #pragma unroll
;   for (int i = 0; i < NS; ++i) {
;     const u32x4 w = __builtin_bit_cast(u32x4, qf[i]); u32x4 o;
;     o.x = cvt_pk_bf16(bf_lo(w.x) * sc, bf_hi(w.x) * sc); o.y = cvt_pk_bf16(bf_lo(w.y) * sc, bf_hi(w.y) * sc);
;     o.z = cvt_pk_bf16(bf_lo(w.z) * sc, bf_hi(w.z) * sc); o.w = cvt_pk_bf16(bf_lo(w.w) * sc, bf_hi(w.w) * sc);
;     qf[i] = __builtin_bit_cast(bf16x8, o);
;   }
.LBB0_99:
	s_xor_b64 s[10:11], s[12:13], -1
	s_lshl_b64 s[14:15], s[14:15], 1
	v_mov_b32_e32 v24, v163
	s_add_u32 s14, s22, s14
	s_addc_u32 s15, s23, s15
	v_readfirstlane_b32 s18, v24
	s_ashr_i32 s18, s18, 6
	s_lshl_b32 s45, s18, 5
	v_and_b32_e32 v0, 63, v24
	s_lshl_b32 s18, s18, 10
	v_lshl_or_b32 v8, v0, 4, s18
	v_ashrrev_i32_e32 v0, 31, v8
	v_lshrrev_b32_e32 v0, 25, v0
	v_add_u32_e32 v0, v8, v0
	v_ashrrev_i32_e32 v3, 7, v0
	v_and_b32_e32 v0, 0xffffff80, v0
	v_sub_u32_e32 v0, v8, v0
	v_ashrrev_i32_e32 v0, 4, v0
	v_lshrrev_b32_e32 v4, 1, v3
	v_bitop3_b32 v9, v0, v4, 7 bitop3:0x78
	v_lshlrev_b32_e32 v2, 3, v9
	v_mov_b64_e32 v[4:5], s[14:15]
	v_mad_i64_i32 v[6:7], s[14:15], v3, s59, v[4:5]
	v_ashrrev_i32_e32 v3, 31, v2
	v_ashrrev_i32_e32 v0, 8, v8
	v_lshl_add_u64 v[2:3], v[2:3], 1, v[6:7]
	v_lshlrev_b32_e32 v6, 2, v0
	v_and_b32_e32 v10, 3, v24
	v_xor_b32_e32 v6, v6, v24
	v_and_or_b32 v11, v6, 12, v10
	v_mul_hi_i32_i24_e32 v7, 0x1800, v0
	v_mul_i32_i24_e32 v6, 0x1800, v0
	v_lshl_add_u64 v[6:7], s[4:5], 0, v[6:7]
	v_lshlrev_b32_e32 v0, 4, v11
	v_lshl_add_u64 v[18:19], v[6:7], 0, v[0:1]
	v_add_u32_e32 v0, 0x2000, v8
	v_ashrrev_i32_e32 v0, 8, v0
	v_lshlrev_b32_e32 v6, 2, v0
	v_xor_b32_e32 v6, v6, v24
	v_and_or_b32 v8, v6, 12, v10
	v_mul_hi_i32_i24_e32 v7, 0x1800, v0
	v_mul_i32_i24_e32 v6, 0x1800, v0
	v_lshl_add_u64 v[6:7], s[4:5], 0, v[6:7]
	v_lshlrev_b32_e32 v0, 4, v8
	v_cmp_gt_i32_e32 vcc, 8, v9
	v_lshl_add_u64 v[20:21], v[6:7], 0, v[0:1]
	s_waitcnt vmcnt(0)
	s_mov_b64 s[14:15], 0x800
	v_cndmask_b32_e64 v7, -1, 0, vcc
	v_cndmask_b32_e64 v6, v200, 0, vcc
	v_lshl_add_u64 v[22:23], v[2:3], 0, v[6:7]
	v_lshl_add_u64 v[2:3], v[22:23], 0, s[14:15]
	s_add_i32 s46, s18, 0
	s_mov_b32 s14, m0
	s_mov_b32 m0, s46
	s_nop 0
	global_load_lds_dwordx4 v[2:3], off
	s_mov_b32 m0, s14
	s_add_i32 s47, s46, 0x2000
	s_mov_b32 s14, m0
	s_mov_b32 m0, s47
	s_nop 0
	global_load_lds_dwordx4 v[18:19], off
	s_mov_b32 m0, s14
	s_add_i32 s52, s46, 0x4000
	s_mov_b32 s14, m0
	s_mov_b32 m0, s52
	s_nop 0
	global_load_lds_dwordx4 v[20:21], off
	s_mov_b32 m0, s14
	s_mov_b64 s[14:15], 0x60800
	v_lshl_add_u64 v[2:3], v[22:23], 0, s[14:15]
	s_add_i32 s14, s46, 0x6000
	s_mov_b32 s15, m0
	s_mov_b32 m0, s14
	s_nop 0
	global_load_lds_dwordx4 v[2:3], off
	s_mov_b32 m0, s15
	v_lshl_add_u64 v[2:3], v[18:19], 0, s[26:27]
	s_add_i32 s14, s46, 0x8000
	s_mov_b32 s15, m0
	s_mov_b32 m0, s14
	s_nop 0
	global_load_lds_dwordx4 v[2:3], off
	s_mov_b32 m0, s15
	v_lshl_add_u64 v[2:3], v[20:21], 0, s[26:27]
	s_add_i32 s14, s46, 0xa000
	s_mov_b32 s15, m0
	s_mov_b32 m0, s14
	s_nop 0
	global_load_lds_dwordx4 v[2:3], off
	s_mov_b32 m0, s15
	s_mov_b64 s[14:15], 0xc0800
	v_lshl_add_u64 v[2:3], v[22:23], 0, s[14:15]
	s_add_i32 s14, s46, 0xc000
	v_and_b32_e32 v25, 31, v24
	s_add_i32 s45, s45, s40
	s_mov_b32 s15, m0
	s_mov_b32 m0, s14
	s_nop 0
	global_load_lds_dwordx4 v[2:3], off
	s_mov_b32 m0, s15
	v_lshl_add_u64 v[2:3], v[18:19], 0, s[28:29]
	s_add_i32 s14, s46, 0xe000
	v_bfe_u32 v26, v24, 5, 1
	s_mov_b32 s15, m0
	s_mov_b32 m0, s14
	s_nop 0
	global_load_lds_dwordx4 v[2:3], off
	s_mov_b32 m0, s15
	v_lshl_add_u64 v[2:3], v[20:21], 0, s[28:29]
	s_add_i32 s14, s46, 0x10000
	v_or_b32_e32 v212, s45, v25
	s_mov_b32 s15, m0
	s_mov_b32 m0, s14
	s_nop 0
	global_load_lds_dwordx4 v[2:3], off
	s_mov_b32 m0, s15
	v_lshlrev_b32_e32 v0, 4, v26
	v_mad_i64_i32 v[2:3], s[14:15], v212, s59, v[4:5]
	v_lshl_add_u64 v[14:15], v[2:3], 0, v[0:1]
	global_load_dwordx4 v[2:5], v[14:15], off
	global_load_dwordx4 v[6:9], v[14:15], off offset:32
	global_load_dwordx4 v[10:13], v[14:15], off offset:64
	s_nop 0
	global_load_dwordx4 v[14:17], v[14:15], off offset:96
	s_mov_b64 s[14:15], 0x120800
	v_lshlrev_b32_e32 v213, 7, v25
	v_lshlrev_b32_e32 v214, 10, v26
	v_lshlrev_b32_e32 v223, 2, v26
	v_lshl_add_u64 v[166:167], v[20:21], 0, s[30:31]
	v_lshl_add_u64 v[168:169], v[18:19], 0, s[30:31]
	v_lshl_add_u64 v[170:171], v[22:23], 0, s[14:15]
	s_mov_b32 s53, 63
	s_mov_b32 s54, 3
	s_mov_b32 s55, 0
	s_or_b32 s56, s45, 31
	v_mov_b32_e32 v227, 0
	s_mov_b32 s57, s44
	s_mov_b64 s[14:15], 0
	s_mov_b32 s58, 3
	s_waitcnt vmcnt(3)
	s_nop 0
	v_lshlrev_b32_e32 v0, 16, v2
	v_and_b32_e32 v2, 0xffff0000, v2
	v_mul_f32_e32 v2, 0x3e38aa3b, v2
	s_waitcnt vmcnt(2)
	s_waitcnt vmcnt(1)
	s_waitcnt vmcnt(0)
; DI unsigned cvt_pk_bf16(float lo, float hi) { unsigned r; asm volatile("v_cvt_pk_bf16_f32 %0, %1, %2" : "=v"(r) : "v"(lo), "v"(hi)); return r; }
; DI float bf_lo(unsigned w) { return __uint_as_float(w << 16); }
; DI float bf_hi(unsigned w) { return __uint_as_float(w & 0xffff0000u); }
; template <int DK>
; DI void attn_pass(const AttnSrc& s, const int q0, const float sc, LAS unsigned char* lds, f32x16 (&O)[4]) {
;     ...
;   for (int i = 0; i < 4; ++i)
; #pragma unroll
;     for (int j = 0; j < 16; ++j) O[i][j] = 0.f;
;   float mrun = (DK == 64) ? 0.f : -INFINITY, lrun = 0.f;
;     ...
;   for (int i = 0; i < NS; ++i) {
;     const u32x4 w = __builtin_bit_cast(u32x4, qf[i]); u32x4 o;
;     o.x = cvt_pk_bf16(bf_lo(w.x) * sc, bf_hi(w.x) * sc); o.y = cvt_pk_bf16(bf_lo(w.y) * sc, bf_hi(w.y) * sc);
;     o.z = cvt_pk_bf16(bf_lo(w.z) * sc, bf_hi(w.z) * sc); o.w = cvt_pk_bf16(bf_lo(w.w) * sc, bf_hi(w.w) * sc);
;     qf[i] = __builtin_bit_cast(bf16x8, o);
;   }
;   }
;   f32x16 negm;
; #pragma unroll
;   for (int j = 0; j < 16; ++j) negm[j] = 0.f;
;   if (REL) asm volatile("" : "+v"(negm));
;   const int kx = (DK == 64) ? (r & 7) : ((r >> 1) & 7);
;   const int krow = r * ROWB;
;   const int i15 = lane & 15;
;   const int vrow = (4 * h + (i15 >> 2)) * 256 + ((lane >> 4) & 1) * 32 + (lane & 3) * 8;
;   const int vx = (i15 >> 2) & 3;
;   int buf = 0, pbuf = DPF;
	v_lshlrev_b32_e32 v29, 16, v5
	v_mul_f32_e32 v0, 0x3e38aa3b, v0
	v_cvt_pk_bf16_f32 v128, v0, v2
	v_and_b32_e32 v2, 0xffff0000, v5
	v_lshlrev_b32_e32 v27, 16, v3
	v_and_b32_e32 v3, 0xffff0000, v3
	v_lshlrev_b32_e32 v28, 16, v4
	v_and_b32_e32 v4, 0xffff0000, v4
	v_mul_f32_e32 v0, 0x3e38aa3b, v29
	v_mul_f32_e32 v2, 0x3e38aa3b, v2
	v_mul_f32_e32 v27, 0x3e38aa3b, v27
	v_mul_f32_e32 v3, 0x3e38aa3b, v3
	v_mul_f32_e32 v28, 0x3e38aa3b, v28
	v_mul_f32_e32 v4, 0x3e38aa3b, v4
	v_cvt_pk_bf16_f32 v129, v27, v3
	v_cvt_pk_bf16_f32 v130, v28, v4
	v_cvt_pk_bf16_f32 v131, v0, v2
	v_lshlrev_b32_e32 v0, 16, v6
	v_and_b32_e32 v2, 0xffff0000, v6
	v_mul_f32_e32 v0, 0x3e38aa3b, v0
	v_mul_f32_e32 v2, 0x3e38aa3b, v2
	v_cvt_pk_bf16_f32 v132, v0, v2
	v_lshlrev_b32_e32 v0, 16, v7
	v_and_b32_e32 v2, 0xffff0000, v7
	v_mul_f32_e32 v0, 0x3e38aa3b, v0
	v_mul_f32_e32 v2, 0x3e38aa3b, v2
	v_cvt_pk_bf16_f32 v133, v0, v2
	v_lshlrev_b32_e32 v0, 16, v8
	v_and_b32_e32 v2, 0xffff0000, v8
	v_mul_f32_e32 v0, 0x3e38aa3b, v0
	v_mul_f32_e32 v2, 0x3e38aa3b, v2
	v_cvt_pk_bf16_f32 v134, v0, v2
	v_lshlrev_b32_e32 v0, 16, v9
	v_and_b32_e32 v2, 0xffff0000, v9
	v_mul_f32_e32 v0, 0x3e38aa3b, v0
	v_mul_f32_e32 v2, 0x3e38aa3b, v2
	v_cvt_pk_bf16_f32 v135, v0, v2
	v_lshlrev_b32_e32 v0, 16, v10
	v_and_b32_e32 v2, 0xffff0000, v10
	v_mul_f32_e32 v0, 0x3e38aa3b, v0
	v_mul_f32_e32 v2, 0x3e38aa3b, v2
	v_cvt_pk_bf16_f32 v136, v0, v2
	v_lshlrev_b32_e32 v0, 16, v11
	v_and_b32_e32 v2, 0xffff0000, v11
	v_mul_f32_e32 v0, 0x3e38aa3b, v0
	v_mul_f32_e32 v2, 0x3e38aa3b, v2
	v_cvt_pk_bf16_f32 v137, v0, v2
	v_lshlrev_b32_e32 v0, 16, v12
	v_and_b32_e32 v2, 0xffff0000, v12
	v_mul_f32_e32 v0, 0x3e38aa3b, v0
	v_mul_f32_e32 v2, 0x3e38aa3b, v2
	v_cvt_pk_bf16_f32 v138, v0, v2
	v_lshlrev_b32_e32 v0, 16, v13
	v_and_b32_e32 v2, 0xffff0000, v13
	v_mul_f32_e32 v0, 0x3e38aa3b, v0
	v_mul_f32_e32 v2, 0x3e38aa3b, v2
	v_cvt_pk_bf16_f32 v139, v0, v2
	v_lshlrev_b32_e32 v0, 16, v14
	v_and_b32_e32 v2, 0xffff0000, v14
	v_mul_f32_e32 v0, 0x3e38aa3b, v0
	v_mul_f32_e32 v2, 0x3e38aa3b, v2
	v_cvt_pk_bf16_f32 v140, v0, v2
	v_lshlrev_b32_e32 v0, 16, v15
	v_and_b32_e32 v2, 0xffff0000, v15
	v_mul_f32_e32 v0, 0x3e38aa3b, v0
	v_mul_f32_e32 v2, 0x3e38aa3b, v2
	v_cvt_pk_bf16_f32 v141, v0, v2
	v_lshlrev_b32_e32 v0, 16, v16
	v_and_b32_e32 v2, 0xffff0000, v16
	v_mul_f32_e32 v0, 0x3e38aa3b, v0
	v_mul_f32_e32 v2, 0x3e38aa3b, v2
	v_cvt_pk_bf16_f32 v142, v0, v2
	v_lshlrev_b32_e32 v0, 16, v17
	v_and_b32_e32 v2, 0xffff0000, v17
	v_lshlrev_b32_e32 v17, 1, v24
	v_and_b32_e32 v216, 32, v17
	v_lshlrev_b32_e32 v17, 3, v24
	v_bfe_u32 v16, v24, 2, 2
	v_and_b32_e32 v217, 24, v17
	v_bfe_u32 v17, v24, 1, 3
	v_bitop3_b32 v24, v26, v17, 7 bitop3:0x78
	v_lshlrev_b32_e32 v218, 4, v24
	v_bitop3_b32 v24, v26, v17, 2 bitop3:0x36
	v_mul_f32_e32 v0, 0x3e38aa3b, v0
	v_mul_f32_e32 v2, 0x3e38aa3b, v2
	v_mov_b32_e32 v14, v1
	v_mov_b32_e32 v15, v1
	v_lshlrev_b32_e32 v219, 4, v24
	v_bitop3_b32 v24, v26, v17, 4 bitop3:0x36
	v_bitop3_b32 v17, v26, v17, 6 bitop3:0x36
	v_cvt_pk_bf16_f32 v143, v0, v2
	v_mov_b32_e32 v0, v1
	v_mov_b32_e32 v2, v1
	v_mov_b32_e32 v3, v1
	v_mov_b32_e32 v4, v1
	v_mov_b32_e32 v5, v1
	v_mov_b32_e32 v6, v1
	v_mov_b32_e32 v7, v1
	v_mov_b32_e32 v8, v1
	v_mov_b32_e32 v9, v1
	v_mov_b32_e32 v10, v1
	v_mov_b32_e32 v11, v1
	v_mov_b32_e32 v12, v1
	v_mov_b32_e32 v13, v1
	v_mov_b64_e32 v[94:95], v[14:15]
	v_lshlrev_b32_e32 v215, 8, v16
	v_lshlrev_b32_e32 v220, 4, v24
	v_lshlrev_b32_e32 v221, 4, v17
	v_lshlrev_b32_e32 v222, 6, v16
	v_mov_b64_e32 v[30:31], v[14:15]
	v_mov_b64_e32 v[46:47], v[14:15]
	v_mov_b64_e32 v[62:63], v[14:15]
	v_mov_b64_e32 v[78:79], v[14:15]
	v_mov_b64_e32 v[92:93], v[12:13]
	v_mov_b64_e32 v[90:91], v[10:11]
	v_mov_b64_e32 v[88:89], v[8:9]
	v_mov_b64_e32 v[86:87], v[6:7]
	v_mov_b64_e32 v[84:85], v[4:5]
	v_mov_b64_e32 v[82:83], v[2:3]
	v_mov_b64_e32 v[80:81], v[0:1]
	v_xor_b32_e32 v224, 64, v222
	v_xor_b32_e32 v225, 0x80, v222
	v_xor_b32_e32 v226, 0xc0, v222
	v_mov_b64_e32 v[28:29], v[12:13]
	v_mov_b64_e32 v[26:27], v[10:11]
	v_mov_b64_e32 v[24:25], v[8:9]
	v_mov_b64_e32 v[22:23], v[6:7]
	v_mov_b64_e32 v[20:21], v[4:5]
	v_mov_b64_e32 v[18:19], v[2:3]
	v_mov_b64_e32 v[16:17], v[0:1]
	v_mov_b64_e32 v[44:45], v[12:13]
	v_mov_b64_e32 v[42:43], v[10:11]
	v_mov_b64_e32 v[40:41], v[8:9]
	v_mov_b64_e32 v[38:39], v[6:7]
	v_mov_b64_e32 v[36:37], v[4:5]
	v_mov_b64_e32 v[34:35], v[2:3]
	v_mov_b64_e32 v[32:33], v[0:1]
	v_mov_b64_e32 v[60:61], v[12:13]
	v_mov_b64_e32 v[58:59], v[10:11]
	v_mov_b64_e32 v[56:57], v[8:9]
	v_mov_b64_e32 v[54:55], v[6:7]
	v_mov_b64_e32 v[52:53], v[4:5]
	v_mov_b64_e32 v[50:51], v[2:3]
	v_mov_b64_e32 v[48:49], v[0:1]
	v_mov_b64_e32 v[76:77], v[12:13]
	v_mov_b64_e32 v[74:75], v[10:11]
	v_mov_b64_e32 v[72:73], v[8:9]
	v_mov_b64_e32 v[70:71], v[6:7]
	v_mov_b64_e32 v[68:69], v[4:5]
	v_mov_b64_e32 v[66:67], v[2:3]
	v_mov_b64_e32 v[64:65], v[0:1]
	v_mov_b32_e32 v14, 0
	s_branch .LBB0_102
